# Ph5 tiles re-mapped onto the four workgroups that own each 128-row panel; the two grid barriers around Ph5 replaced by panel-local rendezvous (arrive counter + L1 invalidate; relies on the panel's wor
# speedup vs baseline: 1.0010x; 1.0010x over previous
.LBB0_428:
	s_waitcnt vmcnt(0)
	s_barrier
	s_mov_b64 s[0:1], exec
	v_readlane_b32 s2, v252, 9
	v_readlane_b32 s3, v252, 10
	s_and_b64 s[2:3], s[0:1], s[2:3]
	v_readlane_b32 s8, v255, 19
	v_readlane_b32 s9, v255, 18
	s_mov_b64 exec, s[2:3]
	s_cbranch_execz .LBB0_480
	v_readlane_b32 s4, v252, 62
	v_readlane_b32 s5, v252, 63
	v_readlane_b32 s2, v252, 8
	s_lshr_b32 s2, s2, 2
	s_lshl_b32 s2, s2, 2
	s_sub_u32 s4, s4, 0x200
	s_subb_u32 s5, s5, 0
	s_add_u32 s4, s4, s2
	s_addc_u32 s5, s5, 0
	s_waitcnt vmcnt(0) lgkmcnt(0)
	v_mov_b32_e32 v0, 1
	global_atomic_add v1, v199, v0, s[4:5] sc0
	s_waitcnt vmcnt(0)
	v_readfirstlane_b32 s2, v1
	s_nop 3
	s_and_b32 s2, s2, -4
	s_add_u32 s2, s2, 4
	s_mov_b32 s3, 0
.Lls4_spin:
	global_load_dword v1, v199, s[4:5] sc1
	s_waitcnt vmcnt(0)
	v_readfirstlane_b32 s6, v1
	s_nop 3
	s_cmp_ge_u32 s6, s2
	s_cbranch_scc1 .Lls4_done
	s_sleep 1
	s_add_u32 s3, s3, 1
	s_cmp_lt_u32 s3, 0x400
	s_cbranch_scc1 .Lls4_spin
.Lls4_done:
	buffer_inv sc1
	s_waitcnt vmcnt(0)

.LBB0_485:
	s_and_b32 s0, s4, 0x1ff
	s_lshr_b32 s7, s4, 9
	s_and_b32 s1, s0, 3
	s_lshl_b32 s1, s1, 2
	s_or_b32 s7, s7, s1
	s_lshr_b32 s0, s0, 2

.LBB0_496:
	s_waitcnt vmcnt(0)
	s_barrier
	s_mov_b64 s[0:1], exec
	v_readlane_b32 s2, v252, 9
	v_readlane_b32 s3, v252, 10
	s_and_b64 s[2:3], s[0:1], s[2:3]
	s_mov_b64 exec, s[2:3]
	s_cbranch_execz .LBB0_548
	v_readlane_b32 s4, v252, 62
	v_readlane_b32 s5, v252, 63
	v_readlane_b32 s2, v252, 8
	s_lshr_b32 s2, s2, 2
	s_lshl_b32 s2, s2, 2
	s_sub_u32 s4, s4, 0x200
	s_subb_u32 s5, s5, 0
	s_add_u32 s4, s4, s2
	s_addc_u32 s5, s5, 0
	s_waitcnt vmcnt(0) lgkmcnt(0)
	v_mov_b32_e32 v0, 1
	global_atomic_add v1, v199, v0, s[4:5] sc0
	s_waitcnt vmcnt(0)
	v_readfirstlane_b32 s2, v1
	s_nop 3
	s_and_b32 s2, s2, -4
	s_add_u32 s2, s2, 4
	s_mov_b32 s3, 0
